# in-projection mainloops: s_setprio 1 over the MFMA part of each K step, 0 over the wait/barrier/DMA-issue part
# baseline (speedup 1.0000x reference)
.Lp2a_comp:
	v_add_u32_e32 v137, s5, v133
	v_add_u32_e32 v138, s5, v134
	v_add_u32_e32 v139, s5, v135
	v_add_u32_e32 v140, s5, v136
	ds_read_b128 v[214:217], v139
	ds_read_b128 v[218:221], v137
	ds_read_b128 v[222:225], v138
	ds_read_b128 v[226:229], v140
	ds_read_b128 v[230:233], v137 offset:2048
	ds_read_b128 v[234:237], v138 offset:2048
	s_setprio 1
	s_waitcnt lgkmcnt(4)
	v_mfma_f32_32x32x16_bf16 v[112:127], v[214:217], v[218:221], v[112:127]
	s_waitcnt lgkmcnt(1)
	v_mfma_f32_32x32x16_bf16 v[48:63], v[214:217], v[230:233], v[48:63]
	ds_read_b128 v[214:217], v139 offset:2048
	ds_read_b128 v[238:241], v140 offset:2048
	s_waitcnt lgkmcnt(1)
	v_mfma_f32_32x32x16_bf16 v[96:111], v[214:217], v[218:221], v[96:111]
	v_mfma_f32_32x32x16_bf16 v[32:47], v[214:217], v[230:233], v[32:47]
	ds_read_b128 v[214:217], v139 offset:4096
	ds_read_b128 v[242:245], v140 offset:4096
	s_waitcnt lgkmcnt(1)
	v_mfma_f32_32x32x16_bf16 v[80:95], v[214:217], v[218:221], v[80:95]
	v_mfma_f32_32x32x16_bf16 v[16:31], v[214:217], v[230:233], v[16:31]
	ds_read_b128 v[214:217], v139 offset:6144
	ds_read_b128 v[246:249], v140 offset:6144
	s_waitcnt lgkmcnt(1)
	v_mfma_f32_32x32x16_bf16 v[64:79], v[214:217], v[218:221], v[64:79]
	v_mfma_f32_32x32x16_bf16 v[0:15], v[214:217], v[230:233], v[0:15]
	v_mfma_f32_32x32x16_bf16 v[112:127], v[226:229], v[222:225], v[112:127]
	v_mfma_f32_32x32x16_bf16 v[48:63], v[226:229], v[234:237], v[48:63]
	v_mfma_f32_32x32x16_bf16 v[96:111], v[238:241], v[222:225], v[96:111]
	v_mfma_f32_32x32x16_bf16 v[32:47], v[238:241], v[234:237], v[32:47]
	v_mfma_f32_32x32x16_bf16 v[80:95], v[242:245], v[222:225], v[80:95]
	v_mfma_f32_32x32x16_bf16 v[16:31], v[242:245], v[234:237], v[16:31]
	s_waitcnt lgkmcnt(0)
	v_mfma_f32_32x32x16_bf16 v[64:79], v[246:249], v[222:225], v[64:79]
	v_mfma_f32_32x32x16_bf16 v[0:15], v[246:249], v[234:237], v[0:15]
	s_setprio 0
	s_add_u32 s5, s5, 0x6000
	s_cmp_eq_u32 s5, 0x12000
	s_cselect_b32 s5, 0, s5
	s_add_i32 s4, s4, 1
	s_cmp_lg_u32 s4, 32
	s_cbranch_scc1 .Lp2a_top
	s_barrier

.Lp2b_comp:
	v_add_u32_e32 v137, s5, v133
	v_add_u32_e32 v138, s5, v134
	v_add_u32_e32 v139, s5, v135
	v_add_u32_e32 v140, s5, v136
	ds_read_b128 v[174:177], v137
	ds_read_b128 v[214:217], v139
	ds_read_b128 v[218:221], v138
	ds_read_b128 v[222:225], v140
	ds_read_b128 v[226:229], v137 offset:2048
	ds_read_b128 v[230:233], v138 offset:2048
	s_setprio 1
	s_waitcnt lgkmcnt(1)
	v_mfma_f32_32x32x16_bf16 v[48:63], v[226:229], v[214:217], v[48:63]
	v_mfma_f32_32x32x16_bf16 v[112:127], v[174:177], v[214:217], v[112:127]
	ds_read_b128 v[214:217], v139 offset:2048
	ds_read_b128 v[234:237], v140 offset:2048
	s_waitcnt lgkmcnt(1)
	v_mfma_f32_32x32x16_bf16 v[96:111], v[174:177], v[214:217], v[96:111]
	v_mfma_f32_32x32x16_bf16 v[32:47], v[226:229], v[214:217], v[32:47]
	ds_read_b128 v[214:217], v139 offset:4096
	ds_read_b128 v[238:241], v140 offset:4096
	s_waitcnt lgkmcnt(1)
	v_mfma_f32_32x32x16_bf16 v[80:95], v[174:177], v[214:217], v[80:95]
	v_mfma_f32_32x32x16_bf16 v[16:31], v[226:229], v[214:217], v[16:31]
	ds_read_b128 v[214:217], v139 offset:6144
	ds_read_b128 v[242:245], v140 offset:6144
	s_waitcnt lgkmcnt(1)
	v_mfma_f32_32x32x16_bf16 v[64:79], v[174:177], v[214:217], v[64:79]
	v_mfma_f32_32x32x16_bf16 v[0:15], v[226:229], v[214:217], v[0:15]
	v_mfma_f32_32x32x16_bf16 v[112:127], v[218:221], v[222:225], v[112:127]
	v_mfma_f32_32x32x16_bf16 v[48:63], v[230:233], v[222:225], v[48:63]
	v_mfma_f32_32x32x16_bf16 v[96:111], v[218:221], v[234:237], v[96:111]
	v_mfma_f32_32x32x16_bf16 v[32:47], v[230:233], v[234:237], v[32:47]
	v_mfma_f32_32x32x16_bf16 v[80:95], v[218:221], v[238:241], v[80:95]
	v_mfma_f32_32x32x16_bf16 v[16:31], v[230:233], v[238:241], v[16:31]
	s_waitcnt lgkmcnt(0)
	v_mfma_f32_32x32x16_bf16 v[64:79], v[218:221], v[242:245], v[64:79]
	v_mfma_f32_32x32x16_bf16 v[0:15], v[230:233], v[242:245], v[0:15]
	s_setprio 0
	s_add_u32 s5, s5, 0x6000
	s_cmp_eq_u32 s5, 0x12000
	s_cselect_b32 s5, 0, s5
	s_add_i32 s4, s4, 1
	s_cmp_lg_u32 s4, 32
	s_cbranch_scc1 .Lp2b_top
	s_barrier
